# attention tile loops (NSA selected-block, MoBA past-block): next tile committed to LDS mid-step behind the QK MFMAs (in the MFMA->VALU hazard slot) instead of at the step boundary
# baseline (speedup 1.0000x reference)
.LBB0_100:
	s_or_b64 exec, exec, s[4:5]
	v_cmp_gt_i32_e64 s[40:41], 64, v212
	ds_write_b32 v112, v4 offset:33804
	s_and_saveexec_b64 s[4:5], s[40:41]
	v_lshl_add_u32 v3, v212, 2, 0
	ds_write_b32 v3, v1 offset:42240
	s_or_b64 exec, exec, s[4:5]
	v_add_u32_e32 v3, 0x8400, v2
	s_waitcnt lgkmcnt(0)
	s_barrier
	ds_read2_b32 v[32:33], v3 offset1:1
	v_add_u32_e32 v3, 0x8408, v2
	ds_read2_b32 v[30:31], v3 offset1:1
	v_add_u32_e32 v3, 0x8410, v2
	ds_read2_b32 v[26:27], v3 offset1:1
	v_add_u32_e32 v3, 0x8418, v2
	ds_read2_b32 v[28:29], v3 offset1:1
	v_add_u32_e32 v3, 0x8420, v2
	ds_read2_b32 v[24:25], v3 offset1:1
	v_add_u32_e32 v3, 0x8428, v2
	ds_read2_b32 v[22:23], v3 offset1:1
	v_add_u32_e32 v3, 0x8430, v2
	ds_read2_b32 v[18:19], v3 offset1:1
	v_add_u32_e32 v3, 0x8438, v2
	ds_read2_b32 v[20:21], v3 offset1:1
	v_add_u32_e32 v3, 0x8440, v2
	ds_read2_b32 v[16:17], v3 offset1:1
	v_add_u32_e32 v3, 0x8448, v2
	ds_read2_b32 v[14:15], v3 offset1:1
	v_add_u32_e32 v3, 0x8450, v2
	ds_read2_b32 v[10:11], v3 offset1:1
	v_add_u32_e32 v3, 0x8458, v2
	ds_read2_b32 v[12:13], v3 offset1:1
	v_add_u32_e32 v3, 0x8460, v2
	ds_read2_b32 v[8:9], v3 offset1:1
	v_add_u32_e32 v3, 0x8468, v2
	ds_read2_b32 v[6:7], v3 offset1:1
	v_add_u32_e32 v3, 0x8470, v2
	v_add_u32_e32 v2, 0x8478, v2
	v_add_u32_e32 v34, 0x8400, v112
	ds_read2_b32 v[4:5], v3 offset1:1
	ds_read2_b32 v[2:3], v2 offset1:1
	ds_read2_b32 v[34:35], v34 offset1:1
	v_cmp_ne_u32_e64 s[48:49], 0, v37
	v_mul_f32_e32 v47, v190, v70
	v_mul_f32_e32 v49, v190, v71
	v_cmp_lt_u32_e64 s[44:45], 4, v37
	s_waitcnt lgkmcnt(0)
	v_cmp_eq_f32_e64 s[42:43], v32, v34
	v_cmp_gt_f32_e64 s[40:41], v32, v34
	s_and_b64 s[4:5], s[48:49], s[42:43]
	v_cmp_eq_f32_e64 s[42:43], v33, v34
	s_or_b64 s[70:71], s[40:41], s[4:5]
	v_cmp_gt_f32_e64 s[40:41], v33, v34
	s_and_b64 s[4:5], s[48:49], s[42:43]
	s_or_b64 s[4:5], s[40:41], s[4:5]
	v_cmp_eq_f32_e64 s[42:43], v30, v34
	v_cndmask_b32_e64 v70, 0, 1, s[4:5]
	v_cmp_gt_f32_e64 s[40:41], v30, v34
	s_and_b64 s[4:5], s[48:49], s[42:43]
	s_or_b64 s[4:5], s[40:41], s[4:5]
	v_cmp_eq_f32_e64 s[42:43], v31, v34
	v_cndmask_b32_e64 v71, 0, 1, s[4:5]
	v_cmp_gt_f32_e64 s[40:41], v31, v34
	s_and_b64 s[4:5], s[48:49], s[42:43]
	v_cmp_eq_f32_e64 s[42:43], v26, v34
	s_or_b64 s[72:73], s[40:41], s[4:5]
	v_cmp_gt_f32_e64 s[40:41], v26, v34
	s_and_b64 s[4:5], s[42:43], s[44:45]
	s_or_b64 s[4:5], s[40:41], s[4:5]
	v_cmp_eq_f32_e64 s[42:43], v27, v34
	v_cmp_lt_u32_e64 s[64:65], 5, v37
	v_mul_f32_e32 v40, v190, v51
	v_mul_f32_e32 v51, v190, v72
	v_cndmask_b32_e64 v72, 0, 1, s[4:5]
	v_cmp_gt_f32_e64 s[40:41], v27, v34
	s_and_b64 s[4:5], s[42:43], s[64:65]
	v_cmp_eq_f32_e64 s[42:43], v28, v34
	v_cmp_lt_u32_e64 s[44:45], 6, v37
	s_or_b64 s[74:75], s[40:41], s[4:5]
	v_cmp_gt_f32_e64 s[40:41], v28, v34
	s_and_b64 s[4:5], s[42:43], s[44:45]
	s_or_b64 s[4:5], s[40:41], s[4:5]
	v_cmp_eq_f32_e64 s[42:43], v29, v34
	v_cmp_lt_u32_e64 s[52:53], 7, v37
	v_mul_f32_e32 v44, v190, v53
	v_mul_f32_e32 v53, v190, v73
	v_cndmask_b32_e64 v73, 0, 1, s[4:5]
	v_cmp_gt_f32_e64 s[40:41], v29, v34
	s_and_b64 s[4:5], s[42:43], s[52:53]
	v_cmp_eq_f32_e64 s[42:43], v24, v34
	v_cmp_lt_u32_e64 s[44:45], 8, v37
	s_or_b64 s[76:77], s[40:41], s[4:5]
	v_cmp_gt_f32_e64 s[40:41], v24, v34
	s_and_b64 s[4:5], s[42:43], s[44:45]
	s_or_b64 s[4:5], s[40:41], s[4:5]
	v_cmp_eq_f32_e64 s[42:43], v25, v34
	v_cmp_lt_u32_e64 s[62:63], 9, v37
	v_mul_f32_e32 v48, v190, v55
	v_mul_f32_e32 v55, v190, v74
	v_cndmask_b32_e64 v74, 0, 1, s[4:5]
	v_cmp_gt_f32_e64 s[40:41], v25, v34
	s_and_b64 s[4:5], s[42:43], s[62:63]
	v_cmp_eq_f32_e64 s[42:43], v22, v34
	v_cmp_lt_u32_e64 s[44:45], 10, v37
	s_or_b64 s[78:79], s[40:41], s[4:5]
	v_cmp_gt_f32_e64 s[40:41], v22, v34
	s_and_b64 s[4:5], s[42:43], s[44:45]
	s_or_b64 s[4:5], s[40:41], s[4:5]
	v_cmp_eq_f32_e64 s[42:43], v23, v34
	v_cmp_lt_u32_e64 s[50:51], 11, v37
	v_mul_f32_e32 v42, v190, v52
	v_mul_f32_e32 v52, v190, v57
	v_mul_f32_e32 v57, v190, v75
	v_cndmask_b32_e64 v75, 0, 1, s[4:5]
	v_cmp_gt_f32_e64 s[40:41], v23, v34
	s_and_b64 s[4:5], s[42:43], s[50:51]
	v_cmp_eq_f32_e64 s[42:43], v18, v34
	v_cmp_lt_u32_e64 s[44:45], 12, v37
	s_or_b64 s[80:81], s[40:41], s[4:5]
	v_cmp_gt_f32_e64 s[40:41], v18, v34
	s_and_b64 s[4:5], s[42:43], s[44:45]
	s_or_b64 s[4:5], s[40:41], s[4:5]
	v_cmp_eq_f32_e64 s[42:43], v19, v34
	v_cmp_lt_u32_e64 s[60:61], 13, v37
	v_mul_f32_e32 v38, v190, v50
	v_mul_f32_e32 v50, v190, v56
	v_mul_f32_e32 v56, v190, v59
	v_mul_f32_e32 v59, v190, v76
	v_cndmask_b32_e64 v76, 0, 1, s[4:5]
	v_cmp_gt_f32_e64 s[40:41], v19, v34
	s_and_b64 s[4:5], s[42:43], s[60:61]
	v_cmp_eq_f32_e64 s[42:43], v20, v34
	v_cmp_lt_u32_e64 s[44:45], 14, v37
	s_or_b64 s[82:83], s[40:41], s[4:5]
	v_cmp_gt_f32_e64 s[40:41], v20, v34
	s_and_b64 s[4:5], s[42:43], s[44:45]
	s_or_b64 s[4:5], s[40:41], s[4:5]
	v_cmp_eq_f32_e64 s[42:43], v21, v34
	v_cmp_lt_u32_e64 s[46:47], 15, v37
	v_mul_f32_e32 v46, v190, v54
	v_mul_f32_e32 v54, v190, v58
	v_mul_f32_e32 v58, v190, v60
	v_mul_f32_e32 v60, v190, v61
	v_mul_f32_e32 v61, v190, v77
	v_cndmask_b32_e64 v77, 0, 1, s[4:5]
	v_cmp_gt_f32_e64 s[40:41], v21, v34
	s_and_b64 s[4:5], s[42:43], s[46:47]
	v_cmp_eq_f32_e64 s[42:43], v16, v34
	v_cmp_lt_u32_e64 s[44:45], 16, v37
	s_or_b64 s[84:85], s[40:41], s[4:5]
	v_cmp_gt_f32_e64 s[40:41], v16, v34
	s_and_b64 s[4:5], s[42:43], s[44:45]
	s_or_b64 s[4:5], s[40:41], s[4:5]
	v_cmp_eq_f32_e64 s[42:43], v17, v34
	v_cmp_lt_u32_e64 s[58:59], 17, v37
	v_mul_f32_e32 v39, v190, v66
	v_mul_f32_e32 v66, v190, v78
	v_cndmask_b32_e64 v78, 0, 1, s[4:5]
	v_cmp_gt_f32_e64 s[40:41], v17, v34
	s_and_b64 s[4:5], s[42:43], s[58:59]
	v_cmp_eq_f32_e64 s[42:43], v14, v34
	v_cmp_lt_u32_e64 s[44:45], 18, v37
	s_or_b64 s[86:87], s[40:41], s[4:5]
	v_cmp_gt_f32_e64 s[40:41], v14, v34
	s_and_b64 s[4:5], s[42:43], s[44:45]
	s_or_b64 s[4:5], s[40:41], s[4:5]
	v_cmp_eq_f32_e64 s[42:43], v15, v34
	v_cmp_lt_u32_e64 s[44:45], 19, v37
	v_mul_f32_e32 v41, v190, v67
	v_mul_f32_e32 v67, v190, v79
	v_cndmask_b32_e64 v79, 0, 1, s[4:5]
	v_cmp_gt_f32_e64 s[40:41], v15, v34
	s_and_b64 s[4:5], s[42:43], s[44:45]
	v_cmp_eq_f32_e64 s[42:43], v10, v34
	v_cmp_lt_u32_e64 s[54:55], 20, v37
	s_or_b64 s[88:89], s[40:41], s[4:5]
	v_cmp_gt_f32_e64 s[40:41], v10, v34
	s_and_b64 s[4:5], s[42:43], s[54:55]
	s_or_b64 s[4:5], s[40:41], s[4:5]
	v_cmp_eq_f32_e64 s[42:43], v11, v34
	v_cmp_lt_u32_e64 s[56:57], 21, v37
	v_mul_f32_e32 v43, v190, v68
	v_mul_f32_e32 v68, v190, v80
	v_cndmask_b32_e64 v80, 0, 1, s[4:5]
	v_cmp_gt_f32_e64 s[40:41], v11, v34
	s_and_b64 s[4:5], s[42:43], s[56:57]
	v_cmp_eq_f32_e64 s[42:43], v12, v34
	v_cmp_lt_u32_e64 s[54:55], 22, v37
	s_or_b64 s[90:91], s[40:41], s[4:5]
	v_cmp_gt_f32_e64 s[40:41], v12, v34
	s_and_b64 s[4:5], s[42:43], s[54:55]
	s_or_b64 s[4:5], s[40:41], s[4:5]
	v_cmp_eq_f32_e64 s[54:55], v13, v34
	v_cmp_lt_u32_e64 s[42:43], 23, v37
	v_mul_f32_e32 v45, v190, v69
	v_mul_f32_e32 v69, v190, v81
	v_cndmask_b32_e64 v81, 0, 1, s[4:5]
	v_cmp_gt_f32_e64 s[40:41], v13, v34
	s_and_b64 s[4:5], s[54:55], s[42:43]
	v_cmp_eq_f32_e64 s[54:55], v8, v34
	v_cmp_lt_u32_e64 s[94:95], 24, v37
	s_or_b64 s[92:93], s[40:41], s[4:5]
	v_cmp_gt_f32_e64 s[40:41], v8, v34
	s_and_b64 s[4:5], s[54:55], s[94:95]
	s_or_b64 s[4:5], s[40:41], s[4:5]
	v_cmp_eq_f32_e64 s[94:95], v9, v34
	v_cmp_lt_u32_e64 s[54:55], 25, v37
	v_cndmask_b32_e64 v113, 0, 1, s[4:5]
	v_cmp_gt_f32_e64 s[40:41], v9, v34
	s_and_b64 s[4:5], s[94:95], s[54:55]
	v_cmp_eq_f32_e64 s[96:97], v6, v34
	v_cmp_lt_u32_e32 vcc, 26, v37
	s_or_b64 s[94:95], s[40:41], s[4:5]
	v_cmp_gt_f32_e64 s[40:41], v6, v34
	s_and_b64 s[4:5], s[96:97], vcc
	s_or_b64 s[4:5], s[40:41], s[4:5]
	v_cmp_eq_f32_e64 s[96:97], v7, v34
	v_cmp_eq_u32_e64 s[40:41], 28, v37
	v_cndmask_b32_e64 v114, 0, 1, s[4:5]
	v_cmp_gt_f32_e32 vcc, v7, v34
	s_and_b64 s[4:5], s[40:41], s[96:97]
	v_cmp_gt_f32_e64 s[96:97], v4, v34
	s_or_b64 s[4:5], vcc, s[4:5]
	v_cmp_gt_f32_e32 vcc, v2, v34
	v_cndmask_b32_e64 v115, 0, 1, s[96:97]
	v_cmp_gt_f32_e64 s[96:97], v5, v34
	v_cndmask_b32_e64 v116, 0, 1, vcc
	v_cmp_gt_f32_e32 vcc, v3, v34
	v_addc_co_u32_e64 v34, s[96:97], 0, v115, s[96:97]
	s_nop 0
	v_addc_co_u32_e32 v34, vcc, v34, v116, vcc
	v_addc_co_u32_e64 v34, vcc, v34, v70, s[70:71]
	v_addc_co_u32_e64 v34, vcc, v34, v71, s[72:73]
	v_addc_co_u32_e64 v34, vcc, v34, v72, s[74:75]
	v_addc_co_u32_e64 v34, vcc, v34, v73, s[76:77]
	v_addc_co_u32_e64 v34, vcc, v34, v74, s[78:79]
	v_addc_co_u32_e64 v34, vcc, v34, v75, s[80:81]
	v_addc_co_u32_e64 v34, vcc, v34, v76, s[82:83]
	v_addc_co_u32_e64 v34, vcc, v34, v77, s[84:85]
	v_addc_co_u32_e64 v34, vcc, v34, v78, s[86:87]
	v_addc_co_u32_e64 v34, vcc, v34, v79, s[88:89]
	v_addc_co_u32_e64 v34, vcc, v34, v80, s[90:91]
	v_addc_co_u32_e64 v34, vcc, v34, v81, s[92:93]
	v_addc_co_u32_e64 v34, vcc, v34, v113, s[94:95]
	v_addc_co_u32_e64 v34, vcc, v34, v114, s[4:5]
	v_cmp_lt_u32_e32 vcc, 15, v34
	s_or_b64 s[4:5], s[66:67], vcc
	v_lshlrev_b32_e64 v34, v37, 1
	v_cndmask_b32_e64 v34, v34, 0, s[4:5]
	v_cmp_ge_f32_e32 vcc, v32, v35
	v_cmp_eq_f32_e64 s[4:5], v33, v35
	s_and_b64 s[4:5], s[48:49], s[4:5]
	v_cndmask_b32_e64 v70, 0, 1, vcc
	v_cmp_gt_f32_e32 vcc, v33, v35
	s_or_b64 s[4:5], vcc, s[4:5]
	v_cndmask_b32_e64 v71, 0, 1, s[4:5]
	v_cmp_eq_f32_e64 s[4:5], v30, v35
	v_cmp_gt_f32_e32 vcc, v30, v35
	s_and_b64 s[4:5], s[48:49], s[4:5]
	s_or_b64 s[66:67], vcc, s[4:5]
	v_cmp_eq_f32_e64 s[4:5], v31, v35
	v_cmp_gt_f32_e32 vcc, v31, v35
	s_and_b64 s[4:5], s[48:49], s[4:5]
	s_or_b64 s[4:5], vcc, s[4:5]
	v_cndmask_b32_e64 v72, 0, 1, s[4:5]
	v_cmp_eq_f32_e64 s[4:5], v26, v35
	v_cmp_gt_f32_e32 vcc, v26, v35
	s_and_b64 s[4:5], s[48:49], s[4:5]
	s_or_b64 s[70:71], vcc, s[4:5]
	v_cmp_eq_f32_e64 s[4:5], v27, v35
	v_cmp_gt_f32_e32 vcc, v27, v35
	s_and_b64 s[4:5], s[4:5], s[64:65]
	s_or_b64 s[4:5], vcc, s[4:5]
	v_cndmask_b32_e64 v73, 0, 1, s[4:5]
	v_cmp_eq_f32_e64 s[4:5], v28, v35
	v_cmp_gt_f32_e32 vcc, v28, v35
	s_and_b64 s[4:5], s[4:5], s[64:65]
	s_or_b64 s[72:73], vcc, s[4:5]
	v_cmp_eq_f32_e64 s[4:5], v29, v35
	v_cmp_gt_f32_e32 vcc, v29, v35
	s_and_b64 s[4:5], s[4:5], s[52:53]
	s_or_b64 s[4:5], vcc, s[4:5]
	v_cndmask_b32_e64 v74, 0, 1, s[4:5]
	v_cmp_eq_f32_e64 s[4:5], v24, v35
	v_cmp_gt_f32_e32 vcc, v24, v35
	s_and_b64 s[4:5], s[4:5], s[52:53]
	s_or_b64 s[74:75], vcc, s[4:5]
	v_cmp_eq_f32_e64 s[4:5], v25, v35
	v_cmp_gt_f32_e32 vcc, v25, v35
	s_and_b64 s[4:5], s[4:5], s[62:63]
	s_or_b64 s[4:5], vcc, s[4:5]
	v_cndmask_b32_e64 v75, 0, 1, s[4:5]
	v_cmp_eq_f32_e64 s[4:5], v22, v35
	v_cmp_gt_f32_e32 vcc, v22, v35
	s_and_b64 s[4:5], s[4:5], s[62:63]
	v_cmp_eq_f32_e64 s[76:77], v23, v35
	s_or_b64 vcc, vcc, s[4:5]
	v_cmp_gt_f32_e64 s[4:5], v23, v35
	s_and_b64 s[76:77], s[76:77], s[50:51]
	s_or_b64 s[4:5], s[4:5], s[76:77]
	v_cmp_eq_f32_e64 s[76:77], v18, v35
	v_cndmask_b32_e64 v76, 0, 1, s[4:5]
	v_cmp_gt_f32_e64 s[4:5], v18, v35
	s_and_b64 s[76:77], s[76:77], s[50:51]
	v_cmp_eq_f32_e64 s[78:79], v19, v35
	s_or_b64 s[4:5], s[4:5], s[76:77]
	v_cmp_gt_f32_e64 s[76:77], v19, v35
	s_and_b64 s[78:79], s[78:79], s[60:61]
	s_or_b64 s[76:77], s[76:77], s[78:79]
	v_cmp_eq_f32_e64 s[78:79], v20, v35
	v_cndmask_b32_e64 v77, 0, 1, s[76:77]
	v_cmp_gt_f32_e64 s[76:77], v20, v35
	s_and_b64 s[78:79], s[78:79], s[60:61]
	v_cmp_eq_f32_e64 s[80:81], v21, v35
	s_or_b64 s[76:77], s[76:77], s[78:79]
	v_cmp_gt_f32_e64 s[78:79], v21, v35
	s_and_b64 s[80:81], s[80:81], s[46:47]
	s_or_b64 s[78:79], s[78:79], s[80:81]
	v_cmp_eq_f32_e64 s[80:81], v16, v35
	v_cndmask_b32_e64 v78, 0, 1, s[78:79]
	v_cmp_gt_f32_e64 s[78:79], v16, v35
	s_and_b64 s[80:81], s[80:81], s[46:47]
	v_cmp_eq_f32_e64 s[82:83], v17, v35
	s_or_b64 s[78:79], s[78:79], s[80:81]
	v_cmp_gt_f32_e64 s[80:81], v17, v35
	s_and_b64 s[82:83], s[82:83], s[58:59]
	s_or_b64 s[80:81], s[80:81], s[82:83]
	v_cmp_eq_f32_e64 s[82:83], v14, v35
	v_cndmask_b32_e64 v79, 0, 1, s[80:81]
	v_cmp_gt_f32_e64 s[80:81], v14, v35
	s_and_b64 s[82:83], s[82:83], s[58:59]
	v_cmp_eq_f32_e64 s[84:85], v15, v35
	s_or_b64 s[80:81], s[80:81], s[82:83]
	v_cmp_gt_f32_e64 s[82:83], v15, v35
	s_and_b64 s[84:85], s[84:85], s[44:45]
	s_or_b64 s[82:83], s[82:83], s[84:85]
	v_cmp_eq_f32_e64 s[84:85], v10, v35
	v_cndmask_b32_e64 v80, 0, 1, s[82:83]
	v_cmp_gt_f32_e64 s[82:83], v10, v35
	s_and_b64 s[84:85], s[84:85], s[44:45]
	v_cmp_eq_f32_e64 s[86:87], v11, v35
	s_or_b64 s[82:83], s[82:83], s[84:85]
	v_cmp_gt_f32_e64 s[84:85], v11, v35
	s_and_b64 s[86:87], s[86:87], s[56:57]
	s_or_b64 s[84:85], s[84:85], s[86:87]
	v_cmp_eq_f32_e64 s[86:87], v12, v35
	v_cndmask_b32_e64 v81, 0, 1, s[84:85]
	v_cmp_gt_f32_e64 s[84:85], v12, v35
	s_and_b64 s[86:87], s[86:87], s[56:57]
	v_cmp_eq_f32_e64 s[88:89], v13, v35
	s_or_b64 s[84:85], s[84:85], s[86:87]
	v_cmp_gt_f32_e64 s[86:87], v13, v35
	s_and_b64 s[88:89], s[88:89], s[42:43]
	s_or_b64 s[86:87], s[86:87], s[88:89]
	v_cmp_eq_f32_e64 s[88:89], v8, v35
	v_cndmask_b32_e64 v113, 0, 1, s[86:87]
	v_cmp_gt_f32_e64 s[86:87], v8, v35
	s_and_b64 s[88:89], s[88:89], s[42:43]
	v_cmp_eq_f32_e64 s[90:91], v9, v35
	s_or_b64 s[86:87], s[86:87], s[88:89]
	v_cmp_gt_f32_e64 s[88:89], v9, v35
	s_and_b64 s[90:91], s[90:91], s[54:55]
	s_or_b64 s[88:89], s[88:89], s[90:91]
	v_cmp_eq_f32_e64 s[90:91], v6, v35
	v_cndmask_b32_e64 v114, 0, 1, s[88:89]
	v_cmp_gt_f32_e64 s[88:89], v6, v35
	s_and_b64 s[90:91], s[90:91], s[54:55]
	v_cmp_eq_f32_e64 s[92:93], v7, v35
	s_or_b64 s[88:89], s[88:89], s[90:91]
	v_cmp_gt_f32_e64 s[90:91], v7, v35
	s_and_b64 s[92:93], s[40:41], s[92:93]
	s_or_b64 s[90:91], s[90:91], s[92:93]
	v_cmp_eq_f32_e64 s[92:93], v4, v35
	v_cndmask_b32_e64 v115, 0, 1, s[90:91]
	v_cmp_gt_f32_e64 s[90:91], v4, v35
	s_and_b64 s[92:93], s[40:41], s[92:93]
	s_or_b64 s[90:91], s[90:91], s[92:93]
	v_cmp_gt_f32_e64 s[92:93], v5, v35
	v_cmp_gt_f32_e64 s[94:95], v2, v35
	v_and_b32_e32 v136, 8, v194
	v_mul_f32_e32 v62, v190, v62
	v_cndmask_b32_e64 v116, 0, 1, s[94:95]
	v_cmp_gt_f32_e64 s[94:95], v3, v35
	v_addc_co_u32_e64 v35, s[92:93], 0, v70, s[92:93]
	s_nop 0
	v_addc_co_u32_e64 v35, s[92:93], v35, v116, s[94:95]
	v_addc_co_u32_e64 v35, s[66:67], v35, v71, s[66:67]
	v_addc_co_u32_e64 v35, s[66:67], v35, v72, s[70:71]
	v_addc_co_u32_e64 v35, s[66:67], v35, v73, s[72:73]
	v_addc_co_u32_e64 v35, s[66:67], v35, v74, s[74:75]
	v_addc_co_u32_e32 v35, vcc, v35, v75, vcc
	v_addc_co_u32_e64 v35, vcc, v35, v76, s[4:5]
	v_addc_co_u32_e64 v35, vcc, v35, v77, s[76:77]
	v_addc_co_u32_e64 v35, vcc, v35, v78, s[78:79]
	v_addc_co_u32_e64 v35, vcc, v35, v79, s[80:81]
	v_addc_co_u32_e64 v35, vcc, v35, v80, s[82:83]
	v_addc_co_u32_e64 v35, vcc, v35, v81, s[84:85]
	v_addc_co_u32_e64 v35, vcc, v35, v113, s[86:87]
	v_addc_co_u32_e64 v35, vcc, v35, v114, s[88:89]
	v_addc_co_u32_e64 v35, vcc, v35, v115, s[90:91]
	v_cmp_lt_u32_e32 vcc, 15, v35
	s_or_b64 s[0:1], s[0:1], vcc
	v_lshlrev_b32_e64 v35, v37, 2
	v_cndmask_b32_e64 v35, v35, 0, s[0:1]
	v_or_b32_e32 v70, v35, v34
	v_add_u32_e32 v34, 0x8408, v112
	ds_read2_b32 v[34:35], v34 offset1:1
	v_cmp_lt_u32_e64 s[70:71], 9, v111
	v_cmp_lt_u32_e64 s[72:73], 13, v111
	v_cmp_lt_u32_e64 s[74:75], 17, v111
	v_cmp_lt_u32_e64 s[76:77], 21, v111
	s_waitcnt lgkmcnt(0)
	v_cmp_ge_f32_e32 vcc, v33, v34
	v_cmp_ge_f32_e64 s[66:67], v32, v34
	v_cmp_eq_f32_e64 s[0:1], v30, v34
	v_cndmask_b32_e64 v71, 0, 1, vcc
	v_addc_co_u32_e64 v71, vcc, 0, v71, s[66:67]
	v_cmp_gt_f32_e32 vcc, v30, v34
	s_and_b64 s[0:1], s[48:49], s[0:1]
	s_or_b64 s[0:1], vcc, s[0:1]
	v_cndmask_b32_e64 v72, 0, 1, s[0:1]
	v_cmp_eq_f32_e64 s[0:1], v31, v34
	v_cmp_gt_f32_e32 vcc, v31, v34
	s_and_b64 s[0:1], s[48:49], s[0:1]
	v_cmp_eq_f32_e64 s[4:5], v26, v34
	s_or_b64 s[0:1], vcc, s[0:1]
	v_cmp_gt_f32_e32 vcc, v26, v34
	s_and_b64 s[4:5], s[48:49], s[4:5]
	s_or_b64 s[4:5], vcc, s[4:5]
	v_cndmask_b32_e64 v73, 0, 1, s[4:5]
	v_cmp_eq_f32_e64 s[4:5], v27, v34
	v_cmp_lt_u32_e64 s[66:67], 5, v111
	v_cmp_gt_f32_e32 vcc, v27, v34
	s_and_b64 s[4:5], s[4:5], s[66:67]
	s_or_b64 s[66:67], vcc, s[4:5]
	v_cmp_eq_f32_e64 s[4:5], v28, v34
	v_cmp_gt_f32_e32 vcc, v28, v34
	s_and_b64 s[4:5], s[4:5], s[64:65]
	s_or_b64 s[4:5], vcc, s[4:5]
	v_cndmask_b32_e64 v74, 0, 1, s[4:5]
	v_cmp_eq_f32_e64 s[4:5], v29, v34
	v_cmp_gt_f32_e32 vcc, v29, v34
	s_and_b64 s[4:5], s[4:5], s[52:53]
	s_or_b64 s[64:65], vcc, s[4:5]
	v_cmp_eq_f32_e64 s[4:5], v24, v34
	v_cmp_gt_f32_e32 vcc, v24, v34
	s_and_b64 s[4:5], s[4:5], s[52:53]
	s_or_b64 s[4:5], vcc, s[4:5]
	v_cndmask_b32_e64 v75, 0, 1, s[4:5]
	v_cmp_eq_f32_e64 s[4:5], v25, v34
	v_cmp_gt_f32_e32 vcc, v25, v34
	s_and_b64 s[4:5], s[4:5], s[70:71]
	s_or_b64 s[70:71], vcc, s[4:5]
	v_cmp_eq_f32_e64 s[4:5], v22, v34
	v_cmp_gt_f32_e32 vcc, v22, v34
	s_and_b64 s[4:5], s[4:5], s[62:63]
	s_or_b64 s[4:5], vcc, s[4:5]
	v_cndmask_b32_e64 v76, 0, 1, s[4:5]
	v_cmp_eq_f32_e64 s[4:5], v23, v34
	v_cmp_gt_f32_e32 vcc, v23, v34
	s_and_b64 s[4:5], s[4:5], s[50:51]
	s_or_b64 s[62:63], vcc, s[4:5]
	v_cmp_eq_f32_e64 s[4:5], v18, v34
	v_cmp_gt_f32_e32 vcc, v18, v34
	s_and_b64 s[4:5], s[4:5], s[50:51]
	s_or_b64 s[4:5], vcc, s[4:5]
	v_cndmask_b32_e64 v77, 0, 1, s[4:5]
	v_cmp_eq_f32_e64 s[4:5], v19, v34
	v_cmp_gt_f32_e32 vcc, v19, v34
	s_and_b64 s[4:5], s[4:5], s[72:73]
	s_or_b64 s[72:73], vcc, s[4:5]
	v_cmp_eq_f32_e64 s[4:5], v20, v34
	v_cmp_gt_f32_e32 vcc, v20, v34
	s_and_b64 s[4:5], s[4:5], s[60:61]
	s_or_b64 s[4:5], vcc, s[4:5]
	v_cndmask_b32_e64 v78, 0, 1, s[4:5]
	v_cmp_eq_f32_e64 s[4:5], v21, v34
	v_cmp_gt_f32_e32 vcc, v21, v34
	s_and_b64 s[4:5], s[4:5], s[46:47]
	s_or_b64 s[60:61], vcc, s[4:5]
	v_cmp_eq_f32_e64 s[4:5], v16, v34
	v_cmp_gt_f32_e32 vcc, v16, v34
	s_and_b64 s[4:5], s[4:5], s[46:47]
	s_or_b64 s[4:5], vcc, s[4:5]
	v_cndmask_b32_e64 v79, 0, 1, s[4:5]
	v_cmp_eq_f32_e64 s[4:5], v17, v34
	v_cmp_gt_f32_e32 vcc, v17, v34
	s_and_b64 s[4:5], s[4:5], s[74:75]
	s_or_b64 s[74:75], vcc, s[4:5]
	v_cmp_eq_f32_e64 s[4:5], v14, v34
	v_cmp_gt_f32_e32 vcc, v14, v34
	s_and_b64 s[4:5], s[4:5], s[58:59]
	s_or_b64 s[4:5], vcc, s[4:5]
	v_cndmask_b32_e64 v80, 0, 1, s[4:5]
	v_cmp_eq_f32_e64 s[4:5], v15, v34
	v_cmp_gt_f32_e32 vcc, v15, v34
	s_and_b64 s[4:5], s[4:5], s[44:45]
	s_or_b64 s[58:59], vcc, s[4:5]
	v_cmp_eq_f32_e64 s[4:5], v10, v34
	v_cmp_gt_f32_e32 vcc, v10, v34
	s_and_b64 s[4:5], s[4:5], s[44:45]
	s_or_b64 s[4:5], vcc, s[4:5]
	v_cndmask_b32_e64 v81, 0, 1, s[4:5]
	v_cmp_eq_f32_e64 s[4:5], v11, v34
	v_cmp_gt_f32_e32 vcc, v11, v34
	s_and_b64 s[4:5], s[4:5], s[76:77]
	v_cmp_eq_f32_e64 s[76:77], v12, v34
	s_or_b64 vcc, vcc, s[4:5]
	v_cmp_gt_f32_e64 s[4:5], v12, v34
	s_and_b64 s[56:57], s[76:77], s[56:57]
	s_or_b64 s[4:5], s[4:5], s[56:57]
	v_cmp_eq_f32_e64 s[56:57], v13, v34
	v_cndmask_b32_e64 v112, 0, 1, s[4:5]
	v_cmp_gt_f32_e64 s[4:5], v13, v34
	s_and_b64 s[56:57], s[56:57], s[42:43]
	v_cmp_eq_f32_e64 s[76:77], v8, v34
	s_or_b64 s[4:5], s[4:5], s[56:57]
	v_cmp_gt_f32_e64 s[56:57], v8, v34
	s_and_b64 s[76:77], s[76:77], s[42:43]
	s_or_b64 s[56:57], s[56:57], s[76:77]
	v_cmp_eq_f32_e64 s[76:77], v9, v34
	v_cmp_lt_u32_e64 s[78:79], 25, v111
	v_cndmask_b32_e64 v113, 0, 1, s[56:57]
	v_cmp_gt_f32_e64 s[56:57], v9, v34
	s_and_b64 s[76:77], s[76:77], s[78:79]
	v_cmp_eq_f32_e64 s[78:79], v6, v34
	s_or_b64 s[56:57], s[56:57], s[76:77]
	v_cmp_gt_f32_e64 s[76:77], v6, v34
	s_and_b64 s[54:55], s[78:79], s[54:55]
	s_or_b64 s[54:55], s[76:77], s[54:55]
	v_cmp_eq_f32_e64 s[76:77], v7, v34
	v_cndmask_b32_e64 v111, 0, 1, s[54:55]
	v_cmp_gt_f32_e64 s[54:55], v7, v34
	s_and_b64 s[76:77], s[40:41], s[76:77]
	v_cmp_eq_f32_e64 s[78:79], v4, v34
	s_or_b64 s[54:55], s[54:55], s[76:77]
	v_cmp_gt_f32_e64 s[76:77], v4, v34
	s_and_b64 s[78:79], s[40:41], s[78:79]
	s_or_b64 s[76:77], s[76:77], s[78:79]
	v_cmp_eq_f32_e64 s[78:79], v5, v34
	v_cndmask_b32_e64 v114, 0, 1, s[76:77]
	v_cmp_gt_f32_e64 s[76:77], v5, v34
	s_and_b64 s[78:79], s[40:41], s[78:79]
	s_or_b64 s[76:77], s[76:77], s[78:79]
	v_cmp_gt_f32_e64 s[78:79], v2, v34
	v_mul_f32_e32 v63, v190, v63
	v_mul_f32_e32 v64, v190, v64
	v_cndmask_b32_e64 v115, 0, 1, s[78:79]
	v_cmp_gt_f32_e64 s[78:79], v3, v34
	v_mul_f32_e32 v65, v190, v65
	s_nop 0
	v_addc_co_u32_e64 v34, s[78:79], v71, v115, s[78:79]
	v_addc_co_u32_e64 v34, s[0:1], v34, v72, s[0:1]
	v_addc_co_u32_e64 v34, s[0:1], v34, v73, s[66:67]
	v_addc_co_u32_e64 v34, s[0:1], v34, v74, s[64:65]
	v_addc_co_u32_e64 v34, s[0:1], v34, v75, s[70:71]
	v_addc_co_u32_e64 v34, s[0:1], v34, v76, s[62:63]
	v_addc_co_u32_e64 v34, s[0:1], v34, v77, s[72:73]
	v_addc_co_u32_e64 v34, s[0:1], v34, v78, s[60:61]
	v_addc_co_u32_e64 v34, s[0:1], v34, v79, s[74:75]
	v_addc_co_u32_e64 v34, s[0:1], v34, v80, s[58:59]
	v_addc_co_u32_e32 v34, vcc, v34, v81, vcc
	v_addc_co_u32_e64 v34, vcc, v34, v112, s[4:5]
	v_addc_co_u32_e64 v34, vcc, v34, v113, s[56:57]
	v_addc_co_u32_e64 v34, vcc, v34, v111, s[54:55]
	v_addc_co_u32_e64 v34, vcc, v34, v114, s[76:77]
	v_cmp_lt_u32_e32 vcc, 15, v34
	s_or_b64 s[0:1], s[38:39], vcc
	v_lshlrev_b32_e64 v34, v37, 4
	v_cndmask_b32_e64 v34, v34, 0, s[0:1]
	v_cmp_ge_f32_e64 s[0:1], v33, v35
	v_cmp_ge_f32_e32 vcc, v32, v35
	v_cmp_lt_u32_e64 s[4:5], 4, v110
	v_cndmask_b32_e64 v32, 0, 1, s[0:1]
	v_addc_co_u32_e32 v32, vcc, 0, v32, vcc
	v_cmp_ge_f32_e32 vcc, v30, v35
	v_cmp_eq_f32_e64 s[0:1], v31, v35
	s_and_b64 s[0:1], s[48:49], s[0:1]
	v_cndmask_b32_e64 v30, 0, 1, vcc
	v_cmp_gt_f32_e32 vcc, v31, v35
	s_or_b64 s[0:1], vcc, s[0:1]
	v_cndmask_b32_e64 v31, 0, 1, s[0:1]
	v_cmp_eq_f32_e64 s[0:1], v26, v35
	v_cmp_gt_f32_e32 vcc, v26, v35
	s_and_b64 s[0:1], s[0:1], s[4:5]
	v_cmp_eq_f32_e64 s[4:5], v27, v35
	v_cmp_lt_u32_e64 s[38:39], 5, v110
	s_or_b64 s[0:1], vcc, s[0:1]
	v_cmp_gt_f32_e32 vcc, v27, v35
	s_and_b64 s[4:5], s[4:5], s[38:39]
	s_or_b64 s[4:5], vcc, s[4:5]
	v_cndmask_b32_e64 v26, 0, 1, s[4:5]
	v_cmp_eq_f32_e64 s[4:5], v28, v35
	v_cmp_lt_u32_e64 s[38:39], 6, v110
	v_cmp_gt_f32_e32 vcc, v28, v35
	s_and_b64 s[4:5], s[4:5], s[38:39]
	s_or_b64 s[38:39], vcc, s[4:5]
	v_cmp_eq_f32_e64 s[4:5], v29, v35
	v_cmp_gt_f32_e32 vcc, v29, v35
	s_and_b64 s[4:5], s[4:5], s[52:53]
	s_or_b64 s[4:5], vcc, s[4:5]
	v_cndmask_b32_e64 v27, 0, 1, s[4:5]
	v_cmp_eq_f32_e64 s[4:5], v24, v35
	v_cmp_lt_u32_e64 s[48:49], 8, v110
	v_cmp_gt_f32_e32 vcc, v24, v35
	s_and_b64 s[4:5], s[4:5], s[48:49]
	s_or_b64 s[48:49], vcc, s[4:5]
	v_cmp_eq_f32_e64 s[4:5], v25, v35
	v_cmp_lt_u32_e64 s[52:53], 9, v110
	v_cmp_gt_f32_e32 vcc, v25, v35
	s_and_b64 s[4:5], s[4:5], s[52:53]
	s_or_b64 s[4:5], vcc, s[4:5]
	v_cndmask_b32_e64 v24, 0, 1, s[4:5]
	v_cmp_eq_f32_e64 s[4:5], v22, v35
	v_cmp_lt_u32_e64 s[52:53], 10, v110
	v_cmp_gt_f32_e32 vcc, v22, v35
	s_and_b64 s[4:5], s[4:5], s[52:53]
	s_or_b64 s[52:53], vcc, s[4:5]
	v_cmp_eq_f32_e64 s[4:5], v23, v35
	v_cmp_gt_f32_e32 vcc, v23, v35
	s_and_b64 s[4:5], s[4:5], s[50:51]
	s_or_b64 s[4:5], vcc, s[4:5]
	v_cndmask_b32_e64 v22, 0, 1, s[4:5]
	v_cmp_eq_f32_e64 s[4:5], v18, v35
	v_cmp_lt_u32_e64 s[50:51], 12, v110
	v_cmp_gt_f32_e32 vcc, v18, v35
	s_and_b64 s[4:5], s[4:5], s[50:51]
	s_or_b64 s[50:51], vcc, s[4:5]
	v_cmp_eq_f32_e64 s[4:5], v19, v35
	v_cmp_lt_u32_e64 s[54:55], 13, v110
	v_cmp_gt_f32_e32 vcc, v19, v35
	s_and_b64 s[4:5], s[4:5], s[54:55]
	s_or_b64 s[4:5], vcc, s[4:5]
	v_cndmask_b32_e64 v18, 0, 1, s[4:5]
	v_cmp_eq_f32_e64 s[4:5], v20, v35
	v_cmp_lt_u32_e64 s[54:55], 14, v110
	v_cmp_gt_f32_e32 vcc, v20, v35
	s_and_b64 s[4:5], s[4:5], s[54:55]
	s_or_b64 s[54:55], vcc, s[4:5]
	v_cmp_eq_f32_e64 s[4:5], v21, v35
	v_cmp_gt_f32_e32 vcc, v21, v35
	s_and_b64 s[4:5], s[4:5], s[46:47]
	s_or_b64 s[4:5], vcc, s[4:5]
	v_cndmask_b32_e64 v19, 0, 1, s[4:5]
	v_cmp_eq_f32_e64 s[4:5], v16, v35
	v_cmp_lt_u32_e64 s[46:47], 16, v110
	v_cmp_gt_f32_e32 vcc, v16, v35
	s_and_b64 s[4:5], s[4:5], s[46:47]
	s_or_b64 s[46:47], vcc, s[4:5]
	v_cmp_eq_f32_e64 s[4:5], v17, v35
	v_cmp_lt_u32_e64 s[56:57], 17, v110
	v_cmp_gt_f32_e32 vcc, v17, v35
	s_and_b64 s[4:5], s[4:5], s[56:57]
	s_or_b64 s[4:5], vcc, s[4:5]
	v_cndmask_b32_e64 v16, 0, 1, s[4:5]
	v_cmp_eq_f32_e64 s[4:5], v14, v35
	v_cmp_lt_u32_e64 s[56:57], 18, v110
	v_cmp_gt_f32_e32 vcc, v14, v35
	s_and_b64 s[4:5], s[4:5], s[56:57]
	s_or_b64 s[56:57], vcc, s[4:5]
	v_cmp_eq_f32_e64 s[4:5], v15, v35
	v_cmp_gt_f32_e32 vcc, v15, v35
	s_and_b64 s[4:5], s[4:5], s[44:45]
	s_or_b64 s[4:5], vcc, s[4:5]
	v_cndmask_b32_e64 v14, 0, 1, s[4:5]
	v_cmp_eq_f32_e64 s[4:5], v10, v35
	v_cmp_lt_u32_e64 s[44:45], 20, v110
	v_cmp_gt_f32_e32 vcc, v10, v35
	s_and_b64 s[4:5], s[4:5], s[44:45]
	s_or_b64 s[44:45], vcc, s[4:5]
	v_cmp_eq_f32_e64 s[4:5], v11, v35
	v_cmp_lt_u32_e64 s[58:59], 21, v110
	v_cmp_gt_f32_e32 vcc, v11, v35
	s_and_b64 s[4:5], s[4:5], s[58:59]
	s_or_b64 s[4:5], vcc, s[4:5]
	v_cndmask_b32_e64 v10, 0, 1, s[4:5]
	v_cmp_eq_f32_e64 s[4:5], v12, v35
	v_cmp_lt_u32_e64 s[58:59], 22, v110
	v_cmp_gt_f32_e32 vcc, v12, v35
	s_and_b64 s[4:5], s[4:5], s[58:59]
	v_cmp_eq_f32_e64 s[58:59], v13, v35
	s_or_b64 vcc, vcc, s[4:5]
	v_cmp_gt_f32_e64 s[4:5], v13, v35
	s_and_b64 s[42:43], s[58:59], s[42:43]
	s_or_b64 s[4:5], s[4:5], s[42:43]
	v_cmp_eq_f32_e64 s[42:43], v8, v35
	v_cmp_lt_u32_e64 s[58:59], 24, v110
	v_cndmask_b32_e64 v11, 0, 1, s[4:5]
	v_cmp_gt_f32_e64 s[4:5], v8, v35
	s_and_b64 s[42:43], s[42:43], s[58:59]
	v_cmp_eq_f32_e64 s[58:59], v9, v35
	v_cmp_lt_u32_e64 s[60:61], 25, v110
	s_or_b64 s[4:5], s[4:5], s[42:43]
	v_cmp_gt_f32_e64 s[42:43], v9, v35
	s_and_b64 s[58:59], s[58:59], s[60:61]
	s_or_b64 s[42:43], s[42:43], s[58:59]
	v_cmp_eq_f32_e64 s[58:59], v6, v35
	v_cmp_lt_u32_e64 s[60:61], 26, v110
	v_cndmask_b32_e64 v8, 0, 1, s[42:43]
	v_cmp_gt_f32_e64 s[42:43], v6, v35
	s_and_b64 s[58:59], s[58:59], s[60:61]
	v_cmp_eq_f32_e64 s[60:61], v7, v35
	s_or_b64 s[42:43], s[42:43], s[58:59]
	v_cmp_gt_f32_e64 s[58:59], v7, v35
	s_and_b64 s[60:61], s[40:41], s[60:61]
	s_or_b64 s[58:59], s[58:59], s[60:61]
	v_cmp_eq_f32_e64 s[60:61], v4, v35
	v_cmp_lt_u32_e64 s[62:63], 28, v110
	v_cndmask_b32_e64 v6, 0, 1, s[58:59]
	v_cmp_gt_f32_e64 s[58:59], v4, v35
	s_and_b64 s[60:61], s[60:61], s[62:63]
	v_cmp_eq_f32_e64 s[62:63], v5, v35
	v_cmp_lt_u32_e64 s[64:65], 29, v110
	s_or_b64 s[58:59], s[58:59], s[60:61]
	v_cmp_gt_f32_e64 s[60:61], v5, v35
	s_and_b64 s[62:63], s[62:63], s[64:65]
	s_or_b64 s[60:61], s[60:61], s[62:63]
	v_cmp_eq_f32_e64 s[62:63], v2, v35
	v_cndmask_b32_e64 v4, 0, 1, s[60:61]
	v_cmp_gt_f32_e64 s[60:61], v2, v35
	s_and_b64 s[40:41], s[40:41], s[62:63]
	s_or_b64 s[40:41], s[60:61], s[40:41]
	v_cmp_gt_f32_e64 s[60:61], v3, v35
	v_lshl_add_u32 v3, v210, 2, 0
	s_nop 0
	v_addc_co_u32_e64 v2, s[60:61], v32, v30, s[60:61]
	v_addc_co_u32_e64 v2, s[0:1], v2, v31, s[0:1]
	v_addc_co_u32_e64 v2, s[0:1], v2, v26, s[38:39]
	v_addc_co_u32_e64 v2, s[0:1], v2, v27, s[48:49]
	v_addc_co_u32_e64 v2, s[0:1], v2, v24, s[52:53]
	v_addc_co_u32_e64 v2, s[0:1], v2, v22, s[50:51]
	v_addc_co_u32_e64 v2, s[0:1], v2, v18, s[54:55]
	v_addc_co_u32_e64 v2, s[0:1], v2, v19, s[46:47]
	v_addc_co_u32_e64 v2, s[0:1], v2, v16, s[56:57]
	v_addc_co_u32_e64 v2, s[0:1], v2, v14, s[44:45]
	v_addc_co_u32_e32 v2, vcc, v2, v10, vcc
	v_addc_co_u32_e64 v2, vcc, v2, v11, s[4:5]
	v_addc_co_u32_e64 v2, vcc, v2, v8, s[42:43]
	v_addc_co_u32_e64 v2, vcc, v2, v6, s[58:59]
	v_addc_co_u32_e64 v2, vcc, v2, v4, s[40:41]
	v_cmp_lt_u32_e32 vcc, 15, v2
	s_or_b64 s[0:1], s[68:69], vcc
	v_lshlrev_b32_e64 v2, v37, 8
	v_cndmask_b32_e64 v2, v2, 0, s[0:1]
	v_or3_b32 v2, v70, v34, v2
	ds_or_b32 v3, v2 offset:42240
	v_lshlrev_b32_e32 v2, 4, v212
	v_and_b32_e32 v133, 0xffffff80, v2
	v_lshrrev_b32_e32 v2, 4, v212
	v_xor_b32_e32 v4, v2, v212
	v_lshlrev_b32_e32 v4, 4, v4
	v_and_b32_e32 v134, 0x70, v4
	v_and_b32_e32 v4, 6, v212
	v_bfe_u32 v3, v212, 4, 3
	v_bitop3_b32 v2, v2, v4, 7 bitop3:0x6c
	v_lshlrev_b32_e32 v135, 4, v2
	v_bitop3_b32 v2, v4, v3, 1 bitop3:0x36
	s_lshl_b32 s0, s3, 13
	v_lshlrev_b32_e32 v137, 4, v2
	v_bfe_u32 v2, v212, 1, 3
	v_bitop3_b32 v3, v36, v213, 7 bitop3:0x6c
	s_cmp_lt_i32 s3, 6
	s_mov_b32 s1, 0xffff4000
	v_lshlrev_b32_e32 v138, 4, v3
	v_bitop3_b32 v3, v213, v2, 2 bitop3:0x36
	s_cselect_b32 s1, 0x14000, s1
	s_add_i32 s0, s0, 0
	v_lshlrev_b32_e32 v139, 4, v3
	v_bitop3_b32 v3, v213, v2, 4 bitop3:0x36
	v_bitop3_b32 v2, v213, v2, 6 bitop3:0x36
	s_add_i32 s0, s0, s1
	v_lshlrev_b32_e32 v141, 4, v2
	v_and_b32_e32 v2, 7, v212
	v_lshl_add_u32 v132, v178, 2, s0
	s_cmp_eq_u32 s2, 0
	v_lshlrev_b32_e32 v140, 4, v3
	v_lshlrev_b32_e32 v126, 4, v2
	s_waitcnt lgkmcnt(0)
	s_barrier
	ds_write2st64_b32 v132, v38, v40 offset1:1
	ds_write2st64_b32 v132, v39, v41 offset0:16 offset1:17
	ds_write2st64_b32 v132, v42, v44 offset0:2 offset1:3
	ds_write2st64_b32 v132, v43, v45 offset0:18 offset1:19
	ds_write2st64_b32 v132, v46, v48 offset0:4 offset1:5
	ds_write2st64_b32 v132, v47, v49 offset0:20 offset1:21
	ds_write2st64_b32 v132, v50, v52 offset0:6 offset1:7
	ds_write2st64_b32 v132, v51, v53 offset0:22 offset1:23
	ds_write2st64_b32 v132, v54, v56 offset0:8 offset1:9
	ds_write2st64_b32 v132, v55, v57 offset0:24 offset1:25
	ds_write2st64_b32 v132, v58, v60 offset0:10 offset1:11
	ds_write2st64_b32 v132, v59, v61 offset0:26 offset1:27
	ds_write2st64_b32 v132, v62, v63 offset0:12 offset1:13
	ds_write2st64_b32 v132, v66, v67 offset0:28 offset1:29
	ds_write2st64_b32 v132, v64, v65 offset0:14 offset1:15
	ds_write2st64_b32 v132, v68, v69 offset0:30 offset1:31
	s_cbranch_scc1 .LBB0_121
	s_lshl_b32 s0, s33, 2
	s_add_i32 s0, s0, 0
	v_lshl_add_u32 v2, v193, 2, s0
	v_mov_b32_e32 v127, v1
	s_add_u32 s0, s18, s28
	ds_read_b32 v142, v2 offset:42240
	v_lshl_add_u64 v[2:3], v[196:197], 0, v[126:127]
	s_addc_u32 s1, s19, s12
	v_lshl_add_u64 v[2:3], s[0:1], 0, v[2:3]
	s_mov_b64 s[4:5], 0x5d80080
	v_lshl_add_u64 v[128:129], v[2:3], 0, s[4:5]
	v_lshl_add_u64 v[2:3], v[194:195], 1, s[0:1]
	s_mov_b64 s[0:1], 0x5d02000
	v_mov_b32_e32 v16, v1
	v_mov_b32_e32 v17, v1
	v_lshl_add_u64 v[130:131], v[2:3], 0, s[0:1]
	v_mov_b32_e32 v2, v1
	v_mov_b32_e32 v3, v1
	v_mov_b32_e32 v4, v1
	v_mov_b32_e32 v5, v1
	v_mov_b32_e32 v6, v1
	v_mov_b32_e32 v7, v1
	v_mov_b32_e32 v8, v1
	v_mov_b32_e32 v9, v1
	v_mov_b32_e32 v10, v1
	v_mov_b32_e32 v11, v1
	v_mov_b32_e32 v12, v1
	v_mov_b32_e32 v13, v1
	v_mov_b32_e32 v14, v1
	v_mov_b32_e32 v15, v1
	v_mov_b32_e32 v127, 0
	v_mov_b64_e32 v[32:33], v[16:17]
	s_mov_b32 s3, 0
	s_mov_b64 s[0:1], 0
	s_mov_b32 s33, 0
	v_mov_b32_e32 v143, 0
	v_mov_b64_e32 v[30:31], v[14:15]
	v_mov_b64_e32 v[28:29], v[12:13]
	v_mov_b64_e32 v[26:27], v[10:11]
	v_mov_b64_e32 v[24:25], v[8:9]
	v_mov_b64_e32 v[22:23], v[6:7]
	v_mov_b64_e32 v[20:21], v[4:5]
	v_mov_b64_e32 v[18:19], v[2:3]
	v_mov_b32_e32 v34, 0
	v_mov_b32_e32 v35, v127
	v_mov_b32_e32 v36, v127
	v_mov_b32_e32 v37, v127
	v_mov_b32_e32 v38, v127
	v_mov_b32_e32 v39, v127
	v_mov_b32_e32 v40, v127
	v_mov_b32_e32 v41, v127
	v_mov_b32_e32 v42, v127
	v_mov_b32_e32 v43, v127
	v_mov_b32_e32 v44, v127
	v_mov_b32_e32 v45, v127
	v_mov_b32_e32 v46, v127
	v_mov_b32_e32 v47, v127
	v_mov_b32_e32 v48, v127
	v_mov_b32_e32 v49, v127
	v_add_u32_e32 v50, 0, v133
	v_add_u32_e32 v51, v50, v134
	s_waitcnt vmcnt(1)
	ds_write_b128 v51, v[106:109] offset:49152
	v_add3_u32 v51, v50, v135, v136
	v_add3_u32 v50, v50, v137, v136
	s_waitcnt vmcnt(0)
	ds_write_b64 v51, v[102:103] offset:57344
	ds_write_b64 v50, v[104:105] offset:57344
	global_load_dwordx4 v[106:109], v[130:131], off
	global_load_dwordx4 v[102:105], v[128:129], off
	v_lshl_add_u64 v[128:129], v[128:129], 0, s[34:35]
	v_lshl_add_u64 v[130:131], v[130:131], 0, s[26:27]
	s_branch .LBB0_106
.Lsel_nomid:
	s_nop 3
	s_branch .Lsel_mid_done
.LBB0_104:
	s_mov_b64 s[0:1], s[4:5]
	s_add_i32 s43, s33, 1
	s_cmp_eq_u32 s43, s2
	s_cbranch_scc1 .LBB0_105
	s_xor_b32 s42, s45, 0x4000
	v_add_u32_e32 v190, s42, v133
	v_add_u32_e32 v202, v190, v134
	s_waitcnt vmcnt(1)
	ds_write_b128 v202, v[106:109] offset:49152
	v_add3_u32 v202, v190, v135, v136
	v_add3_u32 v190, v190, v137, v136
	s_waitcnt vmcnt(0)
	ds_write_b64 v202, v[102:103] offset:57344
	ds_write_b64 v190, v[104:105] offset:57344
	global_load_dwordx4 v[106:109], v[130:131], off
	global_load_dwordx4 v[102:105], v[128:129], off
	v_lshl_add_u64 v[128:129], v[128:129], 0, s[34:35]
	v_lshl_add_u64 v[130:131], v[130:131], 0, s[26:27]

.LBB0_106:
	s_and_b32 s4, s3, 0x4000
	s_add_i32 s45, s4, 0
	v_lshrrev_b32_e32 v50, s33, v142
	v_and_b32_e32 v50, 1, v50
	v_cmp_eq_u32_e64 s[38:39], 1, v50
	v_bfe_u32 v50, v142, s33, 1
	s_andn2_b64 s[4:5], s[0:1], exec
	s_and_b64 s[40:41], s[0:1], exec
	v_cmp_ne_u32_e32 vcc, 0, v50
	s_or_b64 s[4:5], s[4:5], s[40:41]
	s_waitcnt lgkmcnt(0)
	s_barrier
	s_cbranch_vccz .LBB0_104
	v_add_u32_e32 v50, s45, v0
	s_mov_b32 s44, 0x7f800000
	v_add_u32_e32 v146, v50, v138
	ds_read_b128 v[66:69], v146 offset:49152
	v_add_u32_e32 v147, v50, v139
	ds_read_b128 v[110:113], v147 offset:49152
	v_add_u32_e32 v144, v50, v140
	ds_read_b128 v[114:117], v144 offset:49152
	v_add_u32_e32 v145, v50, v141
	ds_read_b128 v[118:121], v145 offset:49152
	ds_read_b128 v[122:125], v146 offset:53248
	ds_read_b128 v[148:151], v147 offset:53248
	ds_read_b128 v[152:155], v144 offset:53248
	ds_read_b128 v[156:159], v145 offset:53248
	s_waitcnt lgkmcnt(7)
	v_mfma_f32_32x32x16_bf16 v[50:65], v[66:69], v[98:101], v[34:49]
	s_waitcnt lgkmcnt(6)
	v_mfma_f32_32x32x16_bf16 v[50:65], v[110:113], v[86:89], v[50:65]
	s_cmp_lg_u64 vcc, -1
	s_cselect_b64 s[40:41], -1, 0
	s_cmp_eq_u64 vcc, -1
	s_cselect_b64 s[42:43], -1, 0
	s_or_b64 vcc, s[42:43], s[38:39]
	s_waitcnt lgkmcnt(3)
	v_mfma_f32_32x32x16_bf16 v[66:81], v[122:125], v[98:101], v[34:49]
	s_waitcnt lgkmcnt(2)
	v_mfma_f32_32x32x16_bf16 v[66:81], v[148:151], v[86:89], v[66:81]
	v_mfma_f32_32x32x16_bf16 v[50:65], v[114:117], v[82:85], v[50:65]
	s_waitcnt lgkmcnt(1)
	v_mfma_f32_32x32x16_bf16 v[66:81], v[152:155], v[82:85], v[66:81]
	v_mfma_f32_32x32x16_bf16 v[50:65], v[118:121], v[90:93], v[50:65]
	ds_read_b128 v[114:117], v146 offset:57344
	ds_read_b128 v[110:113], v147 offset:57344
	ds_read_b128 v[118:121], v144 offset:57344
	ds_read_b128 v[122:125], v145 offset:57344
	s_waitcnt lgkmcnt(4)
	v_mfma_f32_32x32x16_bf16 v[66:81], v[156:159], v[90:93], v[66:81]
	s_add_i32 s43, s33, 1
	s_cmp_eq_u32 s43, s2
	s_cbranch_scc1 .Lsel_nomid
	s_xor_b32 s42, s45, 0x4000
	v_add_u32_e32 v190, s42, v133
	v_add_u32_e32 v202, v190, v134
	s_waitcnt vmcnt(1)
	ds_write_b128 v202, v[106:109] offset:49152
	v_add3_u32 v202, v190, v135, v136
	v_add3_u32 v190, v190, v137, v136
	s_waitcnt vmcnt(0)
	ds_write_b64 v202, v[102:103] offset:57344
	ds_write_b64 v190, v[104:105] offset:57344
	global_load_dwordx4 v[106:109], v[130:131], off
	global_load_dwordx4 v[102:105], v[128:129], off
	v_lshl_add_u64 v[128:129], v[128:129], 0, s[34:35]
	v_lshl_add_u64 v[130:131], v[130:131], 0, s[26:27]
.Lsel_mid_done:
	v_max3_f32 v149, v50, v51, v52
	v_max3_f32 v149, v149, v53, v54
	v_max3_f32 v149, v149, v55, v56
	v_max3_f32 v149, v149, v57, v58
	v_max3_f32 v149, v149, v59, v60
	v_max3_f32 v149, v149, v61, v62
	v_max3_f32 v149, v149, v63, v64
	v_max3_f32 v150, v66, v67, v68
	v_max3_f32 v150, v150, v69, v70
	v_max3_f32 v150, v150, v71, v72
	v_max3_f32 v150, v150, v73, v74
	v_max3_f32 v150, v150, v75, v76
	v_max3_f32 v150, v150, v77, v78
	v_max3_f32 v150, v150, v79, v80
	v_max3_f32 v148, v149, v150, v65
	v_max_f32_e32 v148, v148, v81
	v_cndmask_b32_e32 v148, v225, v148, vcc
	v_mov_b32_e32 v149, v148
	s_nop 1
	v_permlane32_swap_b32_e32 v148, v149
	v_max_f32_e32 v149, v149, v149
	v_max_f32_e32 v148, v148, v148
	v_max_f32_e32 v148, v148, v149
	v_cndmask_b32_e64 v149, v227, v228, s[0:1]
	v_cmp_gt_f32_e32 vcc, v148, v149
	s_cbranch_vccz .LBB0_109
	s_nop 0
	v_cndmask_b32_e32 v36, 0, v148, vcc
	v_exp_f32_e64 v38, -v36
	v_add_f32_e32 v143, v143, v36
	v_xor_b32_e32 v34, 0x80000000, v143
	v_pk_add_f32 v[50:51], v[50:51], v[36:37] op_sel_hi:[1,0] neg_lo:[0,1] neg_hi:[0,1]
	v_mul_f32_e32 v127, v127, v38
	v_pk_add_f32 v[66:67], v[66:67], v[36:37] op_sel_hi:[1,0] neg_lo:[0,1] neg_hi:[0,1]
	v_pk_add_f32 v[52:53], v[52:53], v[36:37] op_sel_hi:[1,0] neg_lo:[0,1] neg_hi:[0,1]
	v_pk_add_f32 v[68:69], v[68:69], v[36:37] op_sel_hi:[1,0] neg_lo:[0,1] neg_hi:[0,1]
	v_pk_add_f32 v[54:55], v[54:55], v[36:37] op_sel_hi:[1,0] neg_lo:[0,1] neg_hi:[0,1]
	v_pk_add_f32 v[70:71], v[70:71], v[36:37] op_sel_hi:[1,0] neg_lo:[0,1] neg_hi:[0,1]
	v_pk_add_f32 v[56:57], v[56:57], v[36:37] op_sel_hi:[1,0] neg_lo:[0,1] neg_hi:[0,1]
	v_pk_add_f32 v[72:73], v[72:73], v[36:37] op_sel_hi:[1,0] neg_lo:[0,1] neg_hi:[0,1]
	v_pk_add_f32 v[58:59], v[58:59], v[36:37] op_sel_hi:[1,0] neg_lo:[0,1] neg_hi:[0,1]
	v_pk_add_f32 v[74:75], v[74:75], v[36:37] op_sel_hi:[1,0] neg_lo:[0,1] neg_hi:[0,1]
	v_pk_add_f32 v[60:61], v[60:61], v[36:37] op_sel_hi:[1,0] neg_lo:[0,1] neg_hi:[0,1]
	v_pk_add_f32 v[76:77], v[76:77], v[36:37] op_sel_hi:[1,0] neg_lo:[0,1] neg_hi:[0,1]
	v_pk_add_f32 v[62:63], v[62:63], v[36:37] op_sel_hi:[1,0] neg_lo:[0,1] neg_hi:[0,1]
	v_pk_add_f32 v[78:79], v[78:79], v[36:37] op_sel_hi:[1,0] neg_lo:[0,1] neg_hi:[0,1]
	v_pk_mul_f32 v[16:17], v[16:17], v[38:39] op_sel_hi:[1,0]
	v_pk_mul_f32 v[14:15], v[14:15], v[38:39] op_sel_hi:[1,0]
	v_pk_mul_f32 v[12:13], v[12:13], v[38:39] op_sel_hi:[1,0]
	v_pk_mul_f32 v[10:11], v[10:11], v[38:39] op_sel_hi:[1,0]
	v_pk_mul_f32 v[8:9], v[8:9], v[38:39] op_sel_hi:[1,0]
	v_pk_mul_f32 v[6:7], v[6:7], v[38:39] op_sel_hi:[1,0]
	v_pk_mul_f32 v[4:5], v[4:5], v[38:39] op_sel_hi:[1,0]
	v_pk_mul_f32 v[2:3], v[2:3], v[38:39] op_sel_hi:[1,0]
	v_pk_mul_f32 v[32:33], v[32:33], v[38:39] op_sel_hi:[1,0]
	v_pk_mul_f32 v[30:31], v[30:31], v[38:39] op_sel_hi:[1,0]
	v_pk_mul_f32 v[28:29], v[28:29], v[38:39] op_sel_hi:[1,0]
	v_pk_mul_f32 v[26:27], v[26:27], v[38:39] op_sel_hi:[1,0]
	v_pk_mul_f32 v[24:25], v[24:25], v[38:39] op_sel_hi:[1,0]
	v_pk_mul_f32 v[22:23], v[22:23], v[38:39] op_sel_hi:[1,0]
	v_pk_mul_f32 v[20:21], v[20:21], v[38:39] op_sel_hi:[1,0]
	v_pk_mul_f32 v[18:19], v[18:19], v[38:39] op_sel_hi:[1,0]
	v_pk_add_f32 v[64:65], v[64:65], v[36:37] op_sel_hi:[1,0] neg_lo:[0,1] neg_hi:[0,1]
	v_pk_add_f32 v[80:81], v[80:81], v[36:37] op_sel_hi:[1,0] neg_lo:[0,1] neg_hi:[0,1]
	v_mov_b32_e32 v35, v34
	v_mov_b32_e32 v36, v34
	v_mov_b32_e32 v37, v34
	v_mov_b32_e32 v38, v34
	v_mov_b32_e32 v39, v34
	v_mov_b32_e32 v40, v34
	v_mov_b32_e32 v41, v34
	v_mov_b32_e32 v42, v34
	v_mov_b32_e32 v43, v34
	v_mov_b32_e32 v44, v34
	v_mov_b32_e32 v45, v34
	v_mov_b32_e32 v46, v34
	v_mov_b32_e32 v47, v34
	v_mov_b32_e32 v48, v34
	v_mov_b32_e32 v49, v34

.LBB0_358:
	v_lshrrev_b32_e32 v0, 4, v124
	v_xor_b32_e32 v3, v0, v124
	v_lshlrev_b32_e32 v3, 4, v3
	v_and_b32_e32 v155, 0x70, v3
	v_and_b32_e32 v3, 6, v124
	v_bfe_u32 v2, v124, 4, 3
	v_bitop3_b32 v0, v0, v3, 7 bitop3:0x6c
	v_lshlrev_b32_e32 v153, 4, v0
	v_bitop3_b32 v0, v3, v2, 1 bitop3:0x36
	v_lshlrev_b32_e32 v154, 4, v0
	v_lshrrev_b32_e32 v0, 1, v124
	v_bfe_u32 v2, v124, 1, 3
	v_bitop3_b32 v0, v0, v141, 7 bitop3:0x6c
	v_lshlrev_b32_e32 v138, 4, v0
	v_bitop3_b32 v0, v141, v2, 2 bitop3:0x36
	v_lshlrev_b32_e32 v139, 4, v0
	v_bitop3_b32 v0, v141, v2, 4 bitop3:0x36
	v_lshlrev_b32_e32 v137, 4, v0
	v_bitop3_b32 v0, v141, v2, 6 bitop3:0x36
	v_and_b32_e32 v151, 0xffffff80, v125
	v_and_b32_e32 v152, 8, v94
	v_lshlrev_b32_e32 v136, 7, v97
	s_andn2_b64 vcc, exec, s[46:47]
	v_lshlrev_b32_e32 v140, 4, v0
	s_cbranch_vccnz .LBB0_368
	s_lshl_b32 s42, s63, 2
	v_and_b32_e32 v0, 7, v124
	v_lshlrev_b32_e32 v0, 4, v0
	s_add_u32 s0, s30, s28
	v_lshl_add_u64 v[2:3], v[122:123], 0, v[0:1]
	s_addc_u32 s1, s31, s29
	v_lshl_add_u64 v[2:3], s[0:1], 0, v[2:3]
	s_mov_b64 s[30:31], 0x5a00080
	v_lshl_add_u64 v[132:133], v[2:3], 0, s[30:31]
	v_lshl_add_u64 v[2:3], v[94:95], 1, s[0:1]
	s_mov_b64 s[0:1], 0x5802000
	v_mov_b32_e32 v14, v1
	v_mov_b32_e32 v15, v1
	v_lshl_add_u64 v[134:135], v[2:3], 0, s[0:1]
	v_mov_b32_e32 v0, v1
	v_mov_b32_e32 v2, v1
	v_mov_b32_e32 v3, v1
	v_mov_b32_e32 v4, v1
	v_mov_b32_e32 v5, v1
	v_mov_b32_e32 v6, v1
	v_mov_b32_e32 v7, v1
	v_mov_b32_e32 v8, v1
	v_mov_b32_e32 v9, v1
	v_mov_b32_e32 v10, v1
	v_mov_b32_e32 v11, v1
	v_mov_b32_e32 v12, v1
	v_mov_b32_e32 v13, v1
	v_mov_b64_e32 v[46:47], v[14:15]
	v_mov_b64_e32 v[30:31], v[14:15]
	v_mov_b64_e32 v[62:63], v[14:15]
	s_mov_b32 s43, 0
	s_mov_b64 s[30:31], 0
	v_mov_b32_e32 v143, 0
	s_mov_b32 s44, 0
	v_mov_b64_e32 v[44:45], v[12:13]
	v_mov_b64_e32 v[42:43], v[10:11]
	v_mov_b64_e32 v[40:41], v[8:9]
	v_mov_b64_e32 v[38:39], v[6:7]
	v_mov_b64_e32 v[36:37], v[4:5]
	v_mov_b64_e32 v[34:35], v[2:3]
	v_mov_b64_e32 v[32:33], v[0:1]
	v_mov_b64_e32 v[28:29], v[12:13]
	v_mov_b64_e32 v[26:27], v[10:11]
	v_mov_b64_e32 v[24:25], v[8:9]
	v_mov_b64_e32 v[22:23], v[6:7]
	v_mov_b64_e32 v[20:21], v[4:5]
	v_mov_b64_e32 v[18:19], v[2:3]
	v_mov_b64_e32 v[16:17], v[0:1]
	v_mov_b64_e32 v[60:61], v[12:13]
	v_mov_b64_e32 v[58:59], v[10:11]
	v_mov_b64_e32 v[56:57], v[8:9]
	v_mov_b64_e32 v[54:55], v[6:7]
	v_mov_b64_e32 v[52:53], v[4:5]
	v_mov_b64_e32 v[50:51], v[2:3]
	v_mov_b64_e32 v[48:49], v[0:1]
	v_mov_b32_e32 v0, 0
	v_add_u32_e32 v190, 0, v151
	v_add_u32_e32 v202, v190, v155
	s_waitcnt vmcnt(0)
	ds_write_b128 v202, v[114:117] offset:49152
	v_add3_u32 v202, v190, v153, v152
	v_add3_u32 v190, v190, v154, v152
	ds_write_b64 v202, v[118:119] offset:57344
	ds_write_b64 v190, v[120:121] offset:57344
	global_load_dwordx4 v[114:117], v[134:135], off
	global_load_dwordx4 v[118:121], v[132:133], off
	v_lshl_add_u64 v[132:133], v[132:133], 0, s[34:35]
	v_lshl_add_u64 v[134:135], v[134:135], 0, s[26:27]
	s_branch .LBB0_362

.LBB0_360:
	s_mov_b64 s[30:31], s[0:1]
	s_add_i32 s41, s44, 1
	s_cmp_eq_u32 s41, s42
	s_cbranch_scc1 .LBB0_361
	s_xor_b32 s40, s46, 0x4000
	v_add_u32_e32 v190, s40, v151
	v_add_u32_e32 v202, v190, v155
	s_waitcnt vmcnt(0)
	ds_write_b128 v202, v[114:117] offset:49152
	v_add3_u32 v202, v190, v153, v152
	v_add3_u32 v190, v190, v154, v152
	ds_write_b64 v202, v[118:119] offset:57344
	ds_write_b64 v190, v[120:121] offset:57344
	global_load_dwordx4 v[114:117], v[134:135], off
	global_load_dwordx4 v[118:121], v[132:133], off
	v_lshl_add_u64 v[132:133], v[132:133], 0, s[34:35]
	v_lshl_add_u64 v[134:135], v[134:135], 0, s[26:27]
.LBB0_361:
	s_add_i32 s44, s44, 1
	s_addk_i32 s43, 0x4000
	s_cmp_eq_u32 s42, s44
	s_cbranch_scc1 .LBB0_369
.LBB0_362:
	s_and_b32 s0, s43, 0x4000
	s_add_i32 s46, s0, 0
	s_lshr_b32 s0, s44, 2
	v_lshrrev_b32_e32 v2, s0, v144
	v_and_b32_e32 v2, 1, v2
	v_cmp_eq_u32_e64 s[36:37], 1, v2
	v_bfe_u32 v2, v144, s0, 1
	s_andn2_b64 s[0:1], s[30:31], exec
	s_and_b64 s[38:39], s[30:31], exec
	v_cmp_ne_u32_e32 vcc, 0, v2
	s_or_b64 s[0:1], s[0:1], s[38:39]
	s_waitcnt lgkmcnt(0)
	s_barrier
	s_cbranch_vccz .LBB0_360
	v_add_u32_e32 v15, s46, v136
	s_mov_b32 s45, 0x7f800000
	v_add_u32_e32 v145, v15, v138
	ds_read_b128 v[2:5], v145 offset:49152
	v_add_u32_e32 v146, v15, v139
	ds_read_b128 v[6:9], v146 offset:49152
	v_add_u32_e32 v14, v15, v137
	ds_read_b128 v[10:13], v14 offset:49152
	v_add_u32_e32 v15, v15, v140
	ds_read_b128 v[122:125], v15 offset:49152
	ds_read_b128 v[156:159], v145 offset:53248
	ds_read_b128 v[160:163], v146 offset:53248
	ds_read_b128 v[164:167], v14 offset:53248
	ds_read_b128 v[168:171], v15 offset:53248
	s_waitcnt lgkmcnt(7)
	v_mfma_f32_32x32x16_bf16 v[64:79], v[2:5], v[110:113], v[48:63]
	s_cmp_lg_u64 vcc, -1
	s_cselect_b64 s[38:39], -1, 0
	s_cmp_eq_u64 vcc, -1
	s_cselect_b64 s[40:41], -1, 0
	s_or_b64 vcc, s[40:41], s[36:37]
	s_waitcnt lgkmcnt(3)
	v_mfma_f32_32x32x16_bf16 v[80:95], v[156:159], v[110:113], v[48:63]
	v_mfma_f32_32x32x16_bf16 v[64:79], v[6:9], v[106:109], v[64:79]
	s_waitcnt lgkmcnt(2)
	v_mfma_f32_32x32x16_bf16 v[80:95], v[160:163], v[106:109], v[80:95]
	v_mfma_f32_32x32x16_bf16 v[64:79], v[10:13], v[102:105], v[64:79]
	s_waitcnt lgkmcnt(1)
	v_mfma_f32_32x32x16_bf16 v[80:95], v[164:167], v[102:105], v[80:95]
	v_mfma_f32_32x32x16_bf16 v[64:79], v[122:125], v[98:101], v[64:79]
	ds_read_b128 v[6:9], v145 offset:57344
	ds_read_b128 v[2:5], v146 offset:57344
	ds_read_b128 v[10:13], v14 offset:57344
	ds_read_b128 v[122:125], v15 offset:57344
	s_waitcnt lgkmcnt(4)
	v_mfma_f32_32x32x16_bf16 v[80:95], v[168:171], v[98:101], v[80:95]
	s_add_i32 s41, s44, 1
	s_cmp_eq_u32 s41, s42
	s_cbranch_scc1 .Lmoba_nomid
	s_xor_b32 s40, s46, 0x4000
	v_add_u32_e32 v190, s40, v151
	v_add_u32_e32 v202, v190, v155
	s_waitcnt vmcnt(0)
	ds_write_b128 v202, v[114:117] offset:49152
	v_add3_u32 v202, v190, v153, v152
	v_add3_u32 v190, v190, v154, v152
	ds_write_b64 v202, v[118:119] offset:57344
	ds_write_b64 v190, v[120:121] offset:57344
	global_load_dwordx4 v[114:117], v[134:135], off
	global_load_dwordx4 v[118:121], v[132:133], off
	v_lshl_add_u64 v[132:133], v[132:133], 0, s[34:35]
	v_lshl_add_u64 v[134:135], v[134:135], 0, s[26:27]
.Lmoba_mid_done:
	v_max3_f32 v148, v64, v65, v66
	v_max3_f32 v148, v148, v67, v68
	v_max3_f32 v148, v148, v69, v70
	v_max3_f32 v148, v148, v71, v72
	v_max3_f32 v148, v148, v73, v74
	v_max3_f32 v148, v148, v75, v76
	v_max3_f32 v148, v148, v77, v78
	v_max3_f32 v149, v80, v81, v82
	v_max3_f32 v149, v149, v83, v84
	v_max3_f32 v149, v149, v85, v86
	v_max3_f32 v149, v149, v87, v88
	v_max3_f32 v149, v149, v89, v90
	v_max3_f32 v149, v149, v91, v92
	v_max3_f32 v149, v149, v93, v94
	v_max3_f32 v147, v148, v149, v79
	v_max_f32_e32 v147, v147, v95
	v_cndmask_b32_e32 v147, v225, v147, vcc
	v_mov_b32_e32 v148, v147
	s_nop 1
	v_permlane32_swap_b32_e32 v147, v148
	v_max_f32_e32 v148, v148, v148
	v_max_f32_e32 v147, v147, v147
	v_max_f32_e32 v147, v147, v148
	v_cndmask_b32_e64 v148, v227, v228, s[30:31]
	v_cmp_gt_f32_e32 vcc, v147, v148
	s_cbranch_vccz .LBB0_365
	s_nop 0
	v_cndmask_b32_e32 v50, 0, v147, vcc
	v_exp_f32_e64 v52, -v50
	v_add_f32_e32 v143, v143, v50
	v_xor_b32_e32 v48, 0x80000000, v143
	v_pk_add_f32 v[64:65], v[64:65], v[50:51] op_sel_hi:[1,0] neg_lo:[0,1] neg_hi:[0,1]
	v_mul_f32_e32 v0, v0, v52
	v_pk_add_f32 v[80:81], v[80:81], v[50:51] op_sel_hi:[1,0] neg_lo:[0,1] neg_hi:[0,1]
	v_pk_add_f32 v[66:67], v[66:67], v[50:51] op_sel_hi:[1,0] neg_lo:[0,1] neg_hi:[0,1]
	v_pk_add_f32 v[82:83], v[82:83], v[50:51] op_sel_hi:[1,0] neg_lo:[0,1] neg_hi:[0,1]
	v_pk_add_f32 v[68:69], v[68:69], v[50:51] op_sel_hi:[1,0] neg_lo:[0,1] neg_hi:[0,1]
	v_pk_add_f32 v[84:85], v[84:85], v[50:51] op_sel_hi:[1,0] neg_lo:[0,1] neg_hi:[0,1]
	v_pk_add_f32 v[70:71], v[70:71], v[50:51] op_sel_hi:[1,0] neg_lo:[0,1] neg_hi:[0,1]
	v_pk_add_f32 v[86:87], v[86:87], v[50:51] op_sel_hi:[1,0] neg_lo:[0,1] neg_hi:[0,1]
	v_pk_add_f32 v[72:73], v[72:73], v[50:51] op_sel_hi:[1,0] neg_lo:[0,1] neg_hi:[0,1]
	v_pk_add_f32 v[88:89], v[88:89], v[50:51] op_sel_hi:[1,0] neg_lo:[0,1] neg_hi:[0,1]
	v_pk_add_f32 v[74:75], v[74:75], v[50:51] op_sel_hi:[1,0] neg_lo:[0,1] neg_hi:[0,1]
	v_pk_add_f32 v[90:91], v[90:91], v[50:51] op_sel_hi:[1,0] neg_lo:[0,1] neg_hi:[0,1]
	v_pk_add_f32 v[76:77], v[76:77], v[50:51] op_sel_hi:[1,0] neg_lo:[0,1] neg_hi:[0,1]
	v_pk_add_f32 v[92:93], v[92:93], v[50:51] op_sel_hi:[1,0] neg_lo:[0,1] neg_hi:[0,1]
	v_pk_mul_f32 v[46:47], v[46:47], v[52:53] op_sel_hi:[1,0]
	v_pk_mul_f32 v[44:45], v[44:45], v[52:53] op_sel_hi:[1,0]
	v_pk_mul_f32 v[42:43], v[42:43], v[52:53] op_sel_hi:[1,0]
	v_pk_mul_f32 v[40:41], v[40:41], v[52:53] op_sel_hi:[1,0]
	v_pk_mul_f32 v[38:39], v[38:39], v[52:53] op_sel_hi:[1,0]
	v_pk_mul_f32 v[36:37], v[36:37], v[52:53] op_sel_hi:[1,0]
	v_pk_mul_f32 v[34:35], v[34:35], v[52:53] op_sel_hi:[1,0]
	v_pk_mul_f32 v[32:33], v[32:33], v[52:53] op_sel_hi:[1,0]
	v_pk_mul_f32 v[30:31], v[30:31], v[52:53] op_sel_hi:[1,0]
	v_pk_mul_f32 v[28:29], v[28:29], v[52:53] op_sel_hi:[1,0]
	v_pk_mul_f32 v[26:27], v[26:27], v[52:53] op_sel_hi:[1,0]
	v_pk_mul_f32 v[24:25], v[24:25], v[52:53] op_sel_hi:[1,0]
	v_pk_mul_f32 v[22:23], v[22:23], v[52:53] op_sel_hi:[1,0]
	v_pk_mul_f32 v[20:21], v[20:21], v[52:53] op_sel_hi:[1,0]
	v_pk_mul_f32 v[18:19], v[18:19], v[52:53] op_sel_hi:[1,0]
	v_pk_mul_f32 v[16:17], v[16:17], v[52:53] op_sel_hi:[1,0]
	v_pk_add_f32 v[78:79], v[78:79], v[50:51] op_sel_hi:[1,0] neg_lo:[0,1] neg_hi:[0,1]
	v_pk_add_f32 v[94:95], v[94:95], v[50:51] op_sel_hi:[1,0] neg_lo:[0,1] neg_hi:[0,1]
	v_mov_b32_e32 v49, v48
	v_mov_b32_e32 v50, v48
	v_mov_b32_e32 v51, v48
	v_mov_b32_e32 v52, v48
	v_mov_b32_e32 v53, v48
	v_mov_b32_e32 v54, v48
	v_mov_b32_e32 v55, v48
	v_mov_b32_e32 v56, v48
	v_mov_b32_e32 v57, v48
	v_mov_b32_e32 v58, v48
	v_mov_b32_e32 v59, v48
	v_mov_b32_e32 v60, v48
	v_mov_b32_e32 v61, v48
	v_mov_b32_e32 v62, v48
	v_mov_b32_e32 v63, v48
